# NA attention: hoisted the 16 exec-masked bias LDS loads out of their serialized wait chain (one wait instead of 16); plus diff-attention loop second half hand-pipelined; no precision change
# baseline (speedup 1.0000x reference)
; DI f32x16 mfma32(bf16x8 a, bf16x8 b, f32x16 c) { return __builtin_amdgcn_mfma_f32_32x32x16_bf16(a, b, c, 0, 0, 0); }
; DI void attn_na_unit(const Params& p, int li, int b, int r, int hp, char* smem) {
;     ...
;     {
;       bf16x8 kf[8];
; #pragma unroll
;       for (int s = 0; s < 4; ++s) {
;         kf[2 * s] = *(const bf16x8*)(ks + r32 * KR + (hs * 64 + s * 16 + hh * 8) * 2);
;         kf[2 * s + 1] = *(const bf16x8*)(ks + (32 + r32) * KR + (hs * 64 + s * 16 + hh * 8) * 2);
;       }
;       __builtin_amdgcn_sched_barrier(0); __builtin_amdgcn_s_setprio(1);
; #pragma unroll
;       for (int s = 0; s < 4; ++s) { s0 = mfma32(kf[2 * s], qf[s], s0); s1 = mfma32(kf[2 * s + 1], qf[s], s1); }
;     __builtin_amdgcn_s_setprio(0);
; }
;     const int drow = rs + kt - r + 7;
;     const float* trow = tab + hs * 465 + drow * 31;
; #pragma unroll
;     for (int i = 0; i < 16; ++i) {
;       const int kc0 = (i & 3) + 8 * (i >> 2) + 4 * hh;
;       const int kc1 = kc0 + 32;
;       const bool v0 = (unsigned)(kc0 - cs) < 16u;
;       const bool v1 = (unsigned)(kc1 - cs) < 16u;
;       const int d0 = v0 ? (kc0 - wq + 15) : 0;
;       const int d1 = v1 ? (kc1 - wq + 15) : 0;
;       const float b0 = trow[d0], b1 = trow[d1];
;       s0[i] = v0 ? s0[i] + b0 : -1e30f;
;       s1[i] = v1 ? s1[i] + b1 : -1e30f;
;     }
.LBB0_1541:
	ds_read_b128 v[150:153], v123
	ds_read_b128 v[154:157], v123 offset:32
	ds_read_b128 v[158:161], v123 offset:8704
	ds_read_b128 v[162:165], v123 offset:8736
	ds_read_b128 v[166:169], v123 offset:64
	ds_read_b128 v[170:173], v123 offset:96
	ds_read_b128 v[174:177], v123 offset:8768
	ds_read_b128 v[178:181], v123 offset:8800
	v_xor_b32_e32 v32, 0x80000000, v128
	v_mov_b32_e32 v33, v32
	v_mov_b32_e32 v34, v32
	v_mov_b32_e32 v35, v32
	v_mov_b32_e32 v36, v32
	v_mov_b32_e32 v37, v32
	v_mov_b32_e32 v38, v32
	v_mov_b32_e32 v39, v32
	v_mov_b32_e32 v40, v32
	v_mov_b32_e32 v41, v32
	v_mov_b32_e32 v42, v32
	v_mov_b32_e32 v43, v32
	v_mov_b32_e32 v44, v32
	v_mov_b32_e32 v45, v32
	v_mov_b32_e32 v46, v32
	v_mov_b32_e32 v47, v32
	s_setprio 1
	s_waitcnt lgkmcnt(7)
	v_mfma_f32_32x32x16_bf16 v[48:63], v[150:153], v[64:67], v[32:47]
	s_waitcnt lgkmcnt(5)
	v_mfma_f32_32x32x16_bf16 v[32:47], v[158:161], v[64:67], v[32:47]
	v_mfma_f32_32x32x16_bf16 v[48:63], v[154:157], v[68:71], v[48:63]
	s_waitcnt lgkmcnt(4)
	v_mfma_f32_32x32x16_bf16 v[32:47], v[162:165], v[68:71], v[32:47]
	s_waitcnt lgkmcnt(3)
	v_mfma_f32_32x32x16_bf16 v[48:63], v[166:169], v[72:75], v[48:63]
	s_waitcnt lgkmcnt(1)
	v_mfma_f32_32x32x16_bf16 v[32:47], v[174:177], v[72:75], v[32:47]
	v_mfma_f32_32x32x16_bf16 v[48:63], v[170:173], v[76:79], v[48:63]
	s_waitcnt lgkmcnt(0)
	v_mfma_f32_32x32x16_bf16 v[32:47], v[178:181], v[76:79], v[32:47]
	s_setprio 0
	v_add_u32_e32 v149, s9, v129
	ds_read_b32 v150, v149 offset:868
	v_mov_b32_e32 v149, 0xf149f2ca
	v_add_u32_e32 v154, s9, v130
	ds_read_b32 v196, v154 offset:868
	ds_read_b32 v197, v154 offset:872
	ds_read_b32 v198, v154 offset:876
	ds_read_b32 v199, v154 offset:880
	ds_read_b32 v200, v154 offset:900
	ds_read_b32 v201, v154 offset:904
	ds_read_b32 v202, v154 offset:908
	ds_read_b32 v203, v154 offset:912
	ds_read_b32 v204, v154 offset:932
	ds_read_b32 v205, v154 offset:936
	ds_read_b32 v206, v154 offset:940
	ds_read_b32 v207, v154 offset:944
	ds_read_b32 v208, v154 offset:964
	ds_read_b32 v209, v154 offset:968
	ds_read_b32 v210, v154 offset:972
	ds_read_b32 v211, v154 offset:976
	v_mov_b32_e32 v151, 0xf149f2ca
	s_waitcnt lgkmcnt(0)
	s_and_saveexec_b64 s[6:7], s[76:77]
	s_cbranch_execz .LBB0_1543
	v_add_f32_e32 v151, v48, v196
.LBB0_1543:
	s_or_b64 exec, exec, s[6:7]
	s_nop 0
	v_add_u32_e32 v48, s9, v131
	ds_read_b32 v152, v48 offset:868
	s_and_saveexec_b64 s[6:7], s[90:91]
	s_cbranch_execz .LBB0_1545
	v_add_f32_e32 v149, v49, v197
.LBB0_1545:
	s_or_b64 exec, exec, s[6:7]
	v_add_u32_e32 v48, s9, v132
	ds_read_b32 v153, v48 offset:868
	v_mov_b32_e32 v48, 0xf149f2ca
	v_mov_b32_e32 v49, 0xf149f2ca
	s_and_saveexec_b64 s[6:7], s[96:97]
	s_cbranch_execz .LBB0_1547
	v_add_f32_e32 v49, v50, v198
.LBB0_1547:
	s_or_b64 exec, exec, s[6:7]
	v_add_u32_e32 v50, s9, v133
	ds_read_b32 v155, v50 offset:868
	s_and_saveexec_b64 s[6:7], s[70:71]
	s_cbranch_execz .LBB0_1549
	v_add_f32_e32 v48, v51, v199
.LBB0_1549:
	s_or_b64 exec, exec, s[6:7]
	v_add_u32_e32 v50, s9, v134
	ds_read_b32 v156, v50 offset:868
	v_mov_b32_e32 v50, 0xf149f2ca
	v_mov_b32_e32 v51, 0xf149f2ca
	s_and_saveexec_b64 s[6:7], s[64:65]
	s_cbranch_execz .LBB0_1551
	v_add_f32_e32 v51, v52, v200
.LBB0_1551:
	s_or_b64 exec, exec, s[6:7]
	v_add_u32_e32 v52, s9, v135
	ds_read_b32 v157, v52 offset:868
	s_and_saveexec_b64 s[6:7], s[66:67]
	s_cbranch_execz .LBB0_1553
	v_add_f32_e32 v50, v53, v201
.LBB0_1553:
	s_or_b64 exec, exec, s[6:7]
	v_add_u32_e32 v52, s9, v136
	ds_read_b32 v158, v52 offset:868
	v_mov_b32_e32 v52, 0xf149f2ca
	v_mov_b32_e32 v53, 0xf149f2ca
	s_and_saveexec_b64 s[6:7], s[60:61]
	s_cbranch_execz .LBB0_1555
	v_add_f32_e32 v53, v54, v202
.LBB0_1555:
	s_or_b64 exec, exec, s[6:7]
	v_add_u32_e32 v54, s9, v137
	ds_read_b32 v159, v54 offset:868
	s_and_saveexec_b64 s[6:7], s[68:69]
	s_cbranch_execz .LBB0_1557
	v_add_f32_e32 v52, v55, v203
.LBB0_1557:
	s_or_b64 exec, exec, s[6:7]
	v_add_u32_e32 v54, s9, v138
	ds_read_b32 v160, v54 offset:868
	v_mov_b32_e32 v54, 0xf149f2ca
	v_mov_b32_e32 v55, 0xf149f2ca
	s_and_saveexec_b64 s[6:7], s[52:53]
	s_cbranch_execz .LBB0_1559
	v_add_f32_e32 v55, v56, v204
.LBB0_1559:
	s_or_b64 exec, exec, s[6:7]
	v_add_u32_e32 v56, s9, v139
	ds_read_b32 v161, v56 offset:868
	s_and_saveexec_b64 s[6:7], s[54:55]
	s_cbranch_execz .LBB0_1561
	v_add_f32_e32 v54, v57, v205
.LBB0_1561:
	s_or_b64 exec, exec, s[6:7]
	v_add_u32_e32 v56, s9, v140
	ds_read_b32 v162, v56 offset:868
	v_mov_b32_e32 v56, 0xf149f2ca
	v_mov_b32_e32 v57, 0xf149f2ca
	s_and_saveexec_b64 s[6:7], s[40:41]
	s_cbranch_execz .LBB0_1563
	v_add_f32_e32 v57, v58, v206
.LBB0_1563:
	s_or_b64 exec, exec, s[6:7]
	v_add_u32_e32 v58, s9, v141
	ds_read_b32 v163, v58 offset:868
	s_and_saveexec_b64 s[6:7], s[42:43]
	s_cbranch_execz .LBB0_1565
	v_add_f32_e32 v56, v59, v207
.LBB0_1565:
	s_or_b64 exec, exec, s[6:7]
	v_add_u32_e32 v58, s9, v142
	ds_read_b32 v164, v58 offset:868
	v_mov_b32_e32 v58, 0xf149f2ca
	v_mov_b32_e32 v59, 0xf149f2ca
	s_and_saveexec_b64 s[6:7], s[36:37]
	s_cbranch_execz .LBB0_1567
	v_add_f32_e32 v59, v60, v208
.LBB0_1567:
	s_or_b64 exec, exec, s[6:7]
	v_add_u32_e32 v60, s9, v143
	ds_read_b32 v165, v60 offset:868
	s_and_saveexec_b64 s[6:7], s[46:47]
	s_cbranch_execz .LBB0_1569
	v_add_f32_e32 v58, v61, v209
.LBB0_1569:
	s_or_b64 exec, exec, s[6:7]
	v_add_u32_e32 v60, s9, v146
	ds_read_b32 v166, v60 offset:868
	v_mov_b32_e32 v60, 0xf149f2ca
	v_mov_b32_e32 v61, 0xf149f2ca
	s_and_saveexec_b64 s[6:7], s[86:87]
	s_cbranch_execz .LBB0_1571
	v_add_f32_e32 v61, v62, v210
.LBB0_1571:
	s_or_b64 exec, exec, s[6:7]
	v_add_u32_e32 v62, s9, v147
	ds_read_b32 v62, v62 offset:868
	s_and_saveexec_b64 s[6:7], s[4:5]
	s_cbranch_execz .LBB0_1573
	v_add_f32_e32 v60, v63, v211
